# fox queue: next unit's ticket taken at the start of the epilogue (atomic round trip hidden)
# speedup vs baseline: 1.0188x; 1.0027x over previous
.LBB0_640:
	s_mov_b32 s100, 0
	s_and_b32 s0, s66, 31
	s_lshl_b32 s1, s86, 3
	s_add_i32 s1, s1, s0
	s_cmp_lt_u32 s0, 8
	s_cselect_b32 s2, s1, 64
	v_readfirstlane_b32 s16, v0
	s_cmp_lt_i32 s2, 64
	v_lshrrev_b32_e32 v143, 7, v0
	s_cbranch_scc1 .LBB0_642
	v_lshlrev_b32_e32 v142, 4, v0
	v_lshrrev_b32_e32 v3, 7, v0
	s_cbranch_execz .LBB0_643
	s_branch .LBB0_650

.LBB0_651:
	s_or_b64 exec, exec, s[2:3]
	s_and_saveexec_b64 s[2:3], s[0:1]
	s_cbranch_execz .Lfox_pf_skip
	global_atomic_add v254, v175, v231, s[6:7] sc0
.Lfox_pf_skip:
	s_or_b64 exec, exec, s[2:3]
	s_mov_b32 s100, 1
	s_waitcnt lgkmcnt(0)
	s_waitcnt lgkmcnt(0)
	ds_read_b128 v[34:37], v226
	ds_read_b128 v[52:55], v226 offset:32
	v_readlane_b32 s36, v253, 20
	v_readlane_b32 s44, v253, 28
	v_readlane_b32 s45, v253, 29
	s_waitcnt lgkmcnt(1)
	v_rcp_f32_e32 v34, v34
	v_readlane_b32 s37, v253, 21
	v_readlane_b32 s38, v253, 22
	v_readlane_b32 s39, v253, 23
	v_mul_f32_e32 v47, v2, v34
	v_rcp_f32_e32 v2, v35
	v_mul_f32_e32 v46, v18, v34
	v_mul_f32_e32 v49, v46, v46
	v_fmac_f32_e32 v49, v47, v47
	v_mul_f32_e32 v45, v3, v2
	v_mul_f32_e32 v44, v19, v2
	v_rcp_f32_e32 v2, v36
	v_mul_f32_e32 v50, v44, v44
	v_fmac_f32_e32 v50, v45, v45
	v_readlane_b32 s40, v253, 24
	v_mul_f32_e32 v43, v4, v2
	v_mul_f32_e32 v42, v20, v2
	v_rcp_f32_e32 v2, v37
	v_mul_f32_e32 v51, v42, v42
	v_fmac_f32_e32 v51, v43, v43
	v_readlane_b32 s41, v253, 25
	v_mul_f32_e32 v41, v5, v2
	v_mul_f32_e32 v40, v21, v2
	s_waitcnt lgkmcnt(0)
	v_rcp_f32_e32 v2, v52
	v_mul_f32_e32 v56, v40, v40
	v_fmac_f32_e32 v56, v41, v41
	v_readlane_b32 s42, v253, 26
	v_mul_f32_e32 v39, v6, v2
	v_mul_f32_e32 v38, v22, v2
	v_rcp_f32_e32 v2, v53
	v_mul_f32_e32 v52, v38, v38
	v_fmac_f32_e32 v52, v39, v39
	v_readlane_b32 s43, v253, 27
	v_mul_f32_e32 v37, v7, v2
	v_mul_f32_e32 v36, v23, v2
	v_rcp_f32_e32 v2, v54
	v_mul_f32_e32 v53, v36, v36
	v_fmac_f32_e32 v53, v37, v37
	v_readlane_b32 s46, v253, 30
	v_mul_f32_e32 v35, v8, v2
	v_mul_f32_e32 v34, v24, v2
	v_rcp_f32_e32 v2, v55
	v_mul_f32_e32 v54, v34, v34
	v_fmac_f32_e32 v54, v35, v35
	v_readlane_b32 s47, v253, 31
	v_mul_f32_e32 v24, v9, v2
	v_mul_f32_e32 v23, v25, v2
	ds_read_b128 v[2:5], v226 offset:64
	v_mul_f32_e32 v25, v23, v23
	v_fmac_f32_e32 v25, v24, v24
	v_readlane_b32 s48, v253, 32
	v_readlane_b32 s49, v253, 33
	s_waitcnt lgkmcnt(0)
	v_rcp_f32_e32 v2, v2
	v_readlane_b32 s50, v253, 34
	v_readlane_b32 s51, v253, 35
	v_mul_f32_e32 v22, v10, v2
	v_mul_f32_e32 v21, v26, v2
	v_rcp_f32_e32 v2, v3
	v_mul_f32_e32 v55, v21, v21
	v_fmac_f32_e32 v55, v22, v22
	v_mul_f32_e32 v20, v11, v2
	v_mul_f32_e32 v19, v27, v2
	v_rcp_f32_e32 v2, v4
	v_mul_f32_e32 v57, v19, v19
	v_fmac_f32_e32 v57, v20, v20
	v_mul_f32_e32 v18, v12, v2
	v_mul_f32_e32 v11, v28, v2
	v_rcp_f32_e32 v2, v5
	v_mul_f32_e32 v58, v11, v11
	v_fmac_f32_e32 v58, v18, v18
	v_mul_f32_e32 v6, v29, v2
	ds_read_b128 v[26:29], v226 offset:96
	v_mul_f32_e32 v7, v13, v2
	v_mul_f32_e32 v13, v6, v6
	v_fmac_f32_e32 v13, v7, v7
	s_waitcnt lgkmcnt(0)
	v_rcp_f32_e32 v2, v26
	v_xor_b32_e32 v26, 1, v240
	v_cmp_lt_i32_e32 vcc, v26, v48
	v_mul_f32_e32 v12, v14, v2
	v_mul_f32_e32 v10, v30, v2
	v_rcp_f32_e32 v2, v27
	v_cndmask_b32_e32 v26, v240, v26, vcc
	v_lshlrev_b32_e32 v26, 2, v26
	v_mul_f32_e32 v14, v10, v10
	v_mul_f32_e32 v8, v31, v2
	ds_bpermute_b32 v31, v26, v52
	v_fmac_f32_e32 v14, v12, v12
	v_mul_f32_e32 v9, v15, v2
	v_rcp_f32_e32 v2, v28
	ds_bpermute_b32 v27, v26, v49
	s_waitcnt lgkmcnt(1)
	v_add_f32_e32 v31, v52, v31
	ds_bpermute_b32 v52, v26, v13
	v_mul_f32_e32 v15, v8, v8
	v_mul_f32_e32 v5, v16, v2
	v_mul_f32_e32 v4, v32, v2
	v_rcp_f32_e32 v2, v29
	s_waitcnt lgkmcnt(0)
	v_add_f32_e32 v13, v13, v52
	ds_bpermute_b32 v52, v26, v14
	v_fmac_f32_e32 v15, v9, v9
	v_add_f32_e32 v27, v49, v27
	ds_bpermute_b32 v28, v26, v50
	ds_bpermute_b32 v29, v26, v51
	ds_bpermute_b32 v49, v26, v25
	s_waitcnt lgkmcnt(3)
	v_add_f32_e32 v14, v14, v52
	ds_bpermute_b32 v52, v26, v15
	v_mul_f32_e32 v3, v17, v2
	v_mul_f32_e32 v2, v33, v2
	v_mul_f32_e32 v16, v4, v4
	v_mul_f32_e32 v17, v2, v2
	v_fmac_f32_e32 v16, v5, v5
	v_fmac_f32_e32 v17, v3, v3
	s_waitcnt lgkmcnt(3)
	v_add_f32_e32 v28, v50, v28
	s_waitcnt lgkmcnt(2)
	v_add_f32_e32 v29, v51, v29
	ds_bpermute_b32 v30, v26, v56
	ds_bpermute_b32 v32, v26, v53
	ds_bpermute_b32 v33, v26, v54
	s_waitcnt lgkmcnt(4)
	v_add_f32_e32 v25, v25, v49
	ds_bpermute_b32 v49, v26, v55
	ds_bpermute_b32 v50, v26, v57
	ds_bpermute_b32 v51, v26, v58
	s_waitcnt lgkmcnt(6)
	v_add_f32_e32 v15, v15, v52
	ds_bpermute_b32 v52, v26, v16
	ds_bpermute_b32 v26, v26, v17
	s_waitcnt lgkmcnt(7)
	v_add_f32_e32 v30, v56, v30
	s_waitcnt lgkmcnt(6)
	v_add_f32_e32 v32, v53, v32
	s_waitcnt lgkmcnt(5)
	v_add_f32_e32 v33, v54, v33
	s_waitcnt lgkmcnt(1)
	v_add_f32_e32 v16, v16, v52
	s_waitcnt lgkmcnt(0)
	v_add_f32_e32 v17, v17, v26
	v_xor_b32_e32 v26, 2, v240
	v_cmp_lt_i32_e32 vcc, v26, v48
	v_add_f32_e32 v49, v55, v49
	v_add_f32_e32 v50, v57, v50
	v_cndmask_b32_e32 v26, v240, v26, vcc
	v_lshlrev_b32_e32 v26, 2, v26
	ds_bpermute_b32 v52, v26, v27
	v_add_f32_e32 v51, v58, v51
	s_waitcnt lgkmcnt(0)
	v_add_f32_e32 v27, v27, v52
	ds_bpermute_b32 v52, v26, v28
	s_waitcnt lgkmcnt(0)
	v_add_f32_e32 v28, v28, v52
	ds_bpermute_b32 v52, v26, v29
	s_waitcnt lgkmcnt(0)
	v_add_f32_e32 v29, v29, v52
	ds_bpermute_b32 v52, v26, v30
	s_waitcnt lgkmcnt(0)
	v_add_f32_e32 v30, v30, v52
	ds_bpermute_b32 v52, v26, v31
	s_waitcnt lgkmcnt(0)
	v_add_f32_e32 v31, v31, v52
	ds_bpermute_b32 v52, v26, v32
	s_waitcnt lgkmcnt(0)
	v_add_f32_e32 v32, v32, v52
	ds_bpermute_b32 v52, v26, v33
	s_waitcnt lgkmcnt(0)
	v_add_f32_e32 v33, v33, v52
	ds_bpermute_b32 v52, v26, v25
	s_waitcnt lgkmcnt(0)
	v_add_f32_e32 v25, v25, v52
	ds_bpermute_b32 v52, v26, v49
	s_waitcnt lgkmcnt(0)
	v_add_f32_e32 v49, v49, v52
	ds_bpermute_b32 v52, v26, v50
	s_waitcnt lgkmcnt(0)
	v_add_f32_e32 v50, v50, v52
	ds_bpermute_b32 v52, v26, v51
	s_waitcnt lgkmcnt(0)
	v_add_f32_e32 v51, v51, v52
	ds_bpermute_b32 v52, v26, v13
	s_waitcnt lgkmcnt(0)
	v_add_f32_e32 v13, v13, v52
	ds_bpermute_b32 v52, v26, v14
	s_waitcnt lgkmcnt(0)
	v_add_f32_e32 v14, v14, v52
	ds_bpermute_b32 v52, v26, v15
	s_waitcnt lgkmcnt(0)
	v_add_f32_e32 v15, v15, v52
	ds_bpermute_b32 v52, v26, v16
	ds_bpermute_b32 v26, v26, v17
	s_waitcnt lgkmcnt(1)
	v_add_f32_e32 v16, v16, v52
	s_waitcnt lgkmcnt(0)
	v_add_f32_e32 v17, v17, v26
	v_xor_b32_e32 v26, 4, v240
	v_cmp_lt_i32_e32 vcc, v26, v48
	s_nop 1
	v_cndmask_b32_e32 v26, v240, v26, vcc
	v_lshlrev_b32_e32 v26, 2, v26
	ds_bpermute_b32 v52, v26, v27
	s_waitcnt lgkmcnt(0)
	v_add_f32_e32 v27, v27, v52
	ds_bpermute_b32 v52, v26, v28
	s_waitcnt lgkmcnt(0)
	v_add_f32_e32 v28, v28, v52
	ds_bpermute_b32 v52, v26, v29
	s_waitcnt lgkmcnt(0)
	v_add_f32_e32 v29, v29, v52
	ds_bpermute_b32 v52, v26, v30
	s_waitcnt lgkmcnt(0)
	v_add_f32_e32 v30, v30, v52
	ds_bpermute_b32 v52, v26, v31
	s_waitcnt lgkmcnt(0)
	v_add_f32_e32 v31, v31, v52
	ds_bpermute_b32 v52, v26, v32
	s_waitcnt lgkmcnt(0)
	v_add_f32_e32 v32, v32, v52
	ds_bpermute_b32 v52, v26, v33
	s_waitcnt lgkmcnt(0)
	v_add_f32_e32 v33, v33, v52
	ds_bpermute_b32 v52, v26, v25
	s_waitcnt lgkmcnt(0)
	v_add_f32_e32 v25, v25, v52
	ds_bpermute_b32 v52, v26, v49
	s_waitcnt lgkmcnt(0)
	v_add_f32_e32 v49, v49, v52
	ds_bpermute_b32 v52, v26, v50
	s_waitcnt lgkmcnt(0)
	v_add_f32_e32 v50, v50, v52
	ds_bpermute_b32 v52, v26, v51
	s_waitcnt lgkmcnt(0)
	v_add_f32_e32 v51, v51, v52
	ds_bpermute_b32 v52, v26, v13
	s_waitcnt lgkmcnt(0)
	v_add_f32_e32 v13, v13, v52
	ds_bpermute_b32 v52, v26, v14
	s_waitcnt lgkmcnt(0)
	v_add_f32_e32 v14, v14, v52
	ds_bpermute_b32 v52, v26, v15
	s_waitcnt lgkmcnt(0)
	v_add_f32_e32 v15, v15, v52
	ds_bpermute_b32 v52, v26, v16
	ds_bpermute_b32 v26, v26, v17
	s_waitcnt lgkmcnt(1)
	v_add_f32_e32 v16, v16, v52
	s_waitcnt lgkmcnt(0)
	v_add_f32_e32 v17, v17, v26
	v_xor_b32_e32 v26, 8, v240
	v_cmp_lt_i32_e32 vcc, v26, v48
	s_nop 1
	v_cndmask_b32_e32 v26, v240, v26, vcc
	v_lshlrev_b32_e32 v26, 2, v26
	ds_bpermute_b32 v52, v26, v27
	s_waitcnt lgkmcnt(0)
	v_add_f32_e32 v27, v27, v52
	ds_bpermute_b32 v52, v26, v28
	s_waitcnt lgkmcnt(0)
	v_add_f32_e32 v28, v28, v52
	ds_bpermute_b32 v52, v26, v29
	s_waitcnt lgkmcnt(0)
	v_add_f32_e32 v29, v29, v52
	ds_bpermute_b32 v52, v26, v30
	s_waitcnt lgkmcnt(0)
	v_add_f32_e32 v30, v30, v52
	ds_bpermute_b32 v52, v26, v31
	s_waitcnt lgkmcnt(0)
	v_add_f32_e32 v31, v31, v52
	ds_bpermute_b32 v52, v26, v32
	s_waitcnt lgkmcnt(0)
	v_add_f32_e32 v32, v32, v52
	ds_bpermute_b32 v52, v26, v33
	s_waitcnt lgkmcnt(0)
	v_add_f32_e32 v52, v33, v52
	ds_bpermute_b32 v33, v26, v25
	s_waitcnt lgkmcnt(0)
	v_add_f32_e32 v25, v25, v33
	ds_bpermute_b32 v33, v26, v49
	s_waitcnt lgkmcnt(0)
	v_add_f32_e32 v53, v49, v33
	ds_bpermute_b32 v33, v26, v50
	s_waitcnt lgkmcnt(0)
	v_add_f32_e32 v50, v50, v33
	ds_bpermute_b32 v33, v26, v51
	s_waitcnt lgkmcnt(0)
	v_add_f32_e32 v51, v51, v33
	ds_bpermute_b32 v33, v26, v13
	s_waitcnt lgkmcnt(0)
	v_add_f32_e32 v13, v13, v33
	ds_bpermute_b32 v33, v26, v14
	s_waitcnt lgkmcnt(0)
	v_add_f32_e32 v14, v14, v33
	ds_bpermute_b32 v33, v26, v15
	s_waitcnt lgkmcnt(0)
	v_add_f32_e32 v15, v15, v33
	ds_bpermute_b32 v33, v26, v16
	ds_bpermute_b32 v26, v26, v17
	s_waitcnt lgkmcnt(1)
	v_add_f32_e32 v16, v16, v33
	s_waitcnt lgkmcnt(0)
	v_add_f32_e32 v54, v17, v26
	v_xor_b32_e32 v17, 16, v240
	v_cmp_lt_i32_e32 vcc, v17, v48
	s_nop 1
	v_cndmask_b32_e32 v17, v240, v17, vcc
	v_lshlrev_b32_e32 v55, 2, v17
	ds_bpermute_b32 v17, v55, v27
	s_waitcnt lgkmcnt(0)
	v_add_f32_e32 v56, v27, v17
	ds_bpermute_b32 v17, v55, v28
	s_waitcnt lgkmcnt(0)
	v_add_f32_e32 v57, v28, v17
	ds_bpermute_b32 v17, v55, v29
	s_waitcnt lgkmcnt(0)
	v_add_f32_e32 v49, v29, v17
	ds_bpermute_b32 v17, v55, v30
	s_waitcnt lgkmcnt(0)
	v_add_f32_e32 v48, v30, v17
	ds_bpermute_b32 v17, v55, v31
	s_waitcnt lgkmcnt(0)
	v_add_f32_e32 v33, v31, v17
	ds_bpermute_b32 v17, v55, v32
	v_fmamk_f32 v33, v33, 0x3c800000, v233
	s_waitcnt lgkmcnt(0)
	v_add_f32_e32 v32, v32, v17
	ds_bpermute_b32 v17, v55, v52
	v_fmamk_f32 v32, v32, 0x3c800000, v233
	s_waitcnt lgkmcnt(0)
	v_add_f32_e32 v31, v52, v17
	ds_bpermute_b32 v17, v55, v25
	v_fmamk_f32 v31, v31, 0x3c800000, v233
	s_waitcnt lgkmcnt(0)
	v_add_f32_e32 v30, v25, v17
	ds_bpermute_b32 v17, v55, v53
	v_fmamk_f32 v30, v30, 0x3c800000, v233
	s_waitcnt lgkmcnt(0)
	v_add_f32_e32 v29, v53, v17
	ds_bpermute_b32 v17, v55, v50
	s_waitcnt lgkmcnt(0)
	v_add_f32_e32 v28, v50, v17
	ds_bpermute_b32 v17, v55, v51
	v_fmamk_f32 v50, v56, 0x3c800000, v233
	v_cmp_gt_f32_e32 vcc, s19, v50
	s_waitcnt lgkmcnt(0)
	v_add_f32_e32 v27, v51, v17
	ds_bpermute_b32 v17, v55, v13
	v_mul_f32_e32 v51, 0x4f800000, v50
	v_cndmask_b32_e32 v50, v50, v51, vcc
	v_sqrt_f32_e32 v51, v50
	s_waitcnt lgkmcnt(0)
	v_add_f32_e32 v26, v13, v17
	ds_bpermute_b32 v13, v55, v14
	v_add_u32_e32 v52, -1, v51
	v_fma_f32 v53, -v52, v51, v50
	v_cmp_ge_f32_e64 s[82:83], 0, v53
	v_add_u32_e32 v53, 1, v51
	s_waitcnt lgkmcnt(0)
	v_add_f32_e32 v25, v14, v13
	ds_bpermute_b32 v13, v55, v15
	v_cndmask_b32_e64 v52, v51, v52, s[82:83]
	v_fma_f32 v51, -v53, v51, v50
	v_cmp_lt_f32_e64 s[82:83], 0, v51
	s_waitcnt lgkmcnt(0)
	v_add_f32_e32 v17, v15, v13
	ds_bpermute_b32 v13, v55, v16
	v_or_b32_e32 v15, s24, v181
	v_cndmask_b32_e64 v51, v52, v53, s[82:83]
	v_mul_f32_e32 v52, 0x37800000, v51
	v_cndmask_b32_e32 v51, v51, v52, vcc
	s_waitcnt lgkmcnt(0)
	v_add_f32_e32 v14, v16, v13
	v_lshlrev_b32_e32 v16, 2, v15
	global_load_dword v15, v16, s[44:45]
	s_nop 0
	global_load_dword v16, v16, s[44:45] offset:128
	v_cmp_class_f32_e32 vcc, v50, v234
	ds_bpermute_b32 v13, v55, v54
	s_waitcnt lgkmcnt(0)
	v_add_f32_e32 v13, v54, v13
	v_cndmask_b32_e32 v50, v51, v50, vcc
	v_div_scale_f32 v51, s[2:3], v50, v50, 1.0
	v_rcp_f32_e32 v52, v51
	s_nop 0
	v_fma_f32 v53, -v51, v52, 1.0
	v_fmac_f32_e32 v52, v53, v52
	v_div_scale_f32 v53, vcc, 1.0, v50, 1.0
	v_mul_f32_e32 v54, v53, v52
	v_fma_f32 v55, -v51, v54, v53
	v_fmac_f32_e32 v54, v55, v52
	v_fma_f32 v51, -v51, v54, v53
	v_div_fmas_f32 v51, v51, v52, v54
	v_div_fixup_f32 v50, v51, v50, 1.0
	v_mul_f32_e32 v47, v47, v50
	v_mul_f32_e32 v46, v46, v50
	s_waitcnt vmcnt(1)
	v_mul_f32_e32 v47, v47, v15
	v_bfe_u32 v51, v47, 16, 1
	v_add3_u32 v47, v47, v51, s22
	s_waitcnt vmcnt(0)
	v_mul_f32_e32 v46, v46, v16
	ds_write_b16_d16_hi v235, v47
	v_bfe_u32 v47, v46, 16, 1
	v_add3_u32 v46, v46, v47, s22
	ds_write_b16_d16_hi v235, v46 offset:64
	v_fmamk_f32 v46, v57, 0x3c800000, v233
	v_cmp_gt_f32_e32 vcc, s19, v46
	v_mul_f32_e32 v47, 0x4f800000, v46
	s_nop 0
	v_cndmask_b32_e32 v46, v46, v47, vcc
	v_sqrt_f32_e32 v47, v46
	s_nop 0
	v_add_u32_e32 v50, -1, v47
	v_fma_f32 v51, -v50, v47, v46
	v_cmp_ge_f32_e64 s[82:83], 0, v51
	v_add_u32_e32 v51, 1, v47
	s_nop 0
	v_cndmask_b32_e64 v50, v47, v50, s[82:83]
	v_fma_f32 v47, -v51, v47, v46
	v_cmp_lt_f32_e64 s[82:83], 0, v47
	s_nop 1
	v_cndmask_b32_e64 v47, v50, v51, s[82:83]
	v_mul_f32_e32 v50, 0x37800000, v47
	v_cndmask_b32_e32 v47, v47, v50, vcc
	v_cmp_class_f32_e32 vcc, v46, v234
	s_nop 1
	v_cndmask_b32_e32 v46, v47, v46, vcc
	v_div_scale_f32 v47, s[2:3], v46, v46, 1.0
	v_rcp_f32_e32 v50, v47
	s_nop 0
	v_fma_f32 v51, -v47, v50, 1.0
	v_fmac_f32_e32 v50, v51, v50
	v_div_scale_f32 v51, vcc, 1.0, v46, 1.0
	v_mul_f32_e32 v52, v51, v50
	v_fma_f32 v53, -v47, v52, v51
	v_fmac_f32_e32 v52, v53, v50
	v_fma_f32 v47, -v47, v52, v51
	v_div_fmas_f32 v47, v47, v50, v52
	v_div_fixup_f32 v46, v47, v46, 1.0
	v_mul_f32_e32 v45, v45, v46
	v_mul_f32_e32 v45, v45, v15
	v_bfe_u32 v47, v45, 16, 1
	v_mul_f32_e32 v44, v44, v46
	v_add3_u32 v45, v45, v47, s22
	v_mul_f32_e32 v44, v44, v16
	ds_write_b16_d16_hi v235, v45 offset:128
	v_bfe_u32 v45, v44, 16, 1
	v_add3_u32 v44, v44, v45, s22
	ds_write_b16_d16_hi v235, v44 offset:192
	v_fmamk_f32 v44, v49, 0x3c800000, v233
	v_cmp_gt_f32_e32 vcc, s19, v44
	v_mul_f32_e32 v45, 0x4f800000, v44
	s_nop 0
	v_cndmask_b32_e32 v44, v44, v45, vcc
	v_sqrt_f32_e32 v45, v44
	s_nop 0
	v_add_u32_e32 v46, -1, v45
	v_fma_f32 v47, -v46, v45, v44
	v_cmp_ge_f32_e64 s[82:83], 0, v47
	v_add_u32_e32 v47, 1, v45
	s_nop 0
	v_cndmask_b32_e64 v46, v45, v46, s[82:83]
	v_fma_f32 v45, -v47, v45, v44
	v_cmp_lt_f32_e64 s[82:83], 0, v45
	s_nop 1
	v_cndmask_b32_e64 v45, v46, v47, s[82:83]
	v_mul_f32_e32 v46, 0x37800000, v45
	v_cndmask_b32_e32 v45, v45, v46, vcc
	v_cmp_class_f32_e32 vcc, v44, v234
	s_nop 1
	v_cndmask_b32_e32 v44, v45, v44, vcc
	v_div_scale_f32 v45, s[2:3], v44, v44, 1.0
	v_rcp_f32_e32 v46, v45
	s_nop 0
	v_fma_f32 v47, -v45, v46, 1.0
	v_fmac_f32_e32 v46, v47, v46
	v_div_scale_f32 v47, vcc, 1.0, v44, 1.0
	v_mul_f32_e32 v49, v47, v46
	v_fma_f32 v50, -v45, v49, v47
	v_fmac_f32_e32 v49, v50, v46
	v_fma_f32 v45, -v45, v49, v47
	v_div_fmas_f32 v45, v45, v46, v49
	v_div_fixup_f32 v44, v45, v44, 1.0
	v_mul_f32_e32 v43, v43, v44
	v_mul_f32_e32 v43, v43, v15
	v_bfe_u32 v45, v43, 16, 1
	v_mul_f32_e32 v42, v42, v44
	v_add3_u32 v43, v43, v45, s22
	v_mul_f32_e32 v42, v42, v16
	ds_write_b16_d16_hi v235, v43 offset:256
	v_bfe_u32 v43, v42, 16, 1
	v_add3_u32 v42, v42, v43, s22
	ds_write_b16_d16_hi v235, v42 offset:320
	v_fmamk_f32 v42, v48, 0x3c800000, v233
	v_cmp_gt_f32_e32 vcc, s19, v42
	v_mul_f32_e32 v43, 0x4f800000, v42
	s_nop 0
	v_cndmask_b32_e32 v42, v42, v43, vcc
	v_sqrt_f32_e32 v43, v42
	s_nop 0
	v_add_u32_e32 v44, -1, v43
	v_fma_f32 v45, -v44, v43, v42
	v_cmp_ge_f32_e64 s[82:83], 0, v45
	v_add_u32_e32 v45, 1, v43
	s_nop 0
	v_cndmask_b32_e64 v44, v43, v44, s[82:83]
	v_fma_f32 v43, -v45, v43, v42
	v_cmp_lt_f32_e64 s[82:83], 0, v43
	s_nop 1
	v_cndmask_b32_e64 v43, v44, v45, s[82:83]
	v_mul_f32_e32 v44, 0x37800000, v43
	v_cndmask_b32_e32 v43, v43, v44, vcc
	v_cmp_class_f32_e32 vcc, v42, v234
	s_nop 1
	v_cndmask_b32_e32 v42, v43, v42, vcc
	v_div_scale_f32 v43, s[2:3], v42, v42, 1.0
	v_rcp_f32_e32 v44, v43
	s_nop 0
	v_fma_f32 v45, -v43, v44, 1.0
	v_fmac_f32_e32 v44, v45, v44
	v_div_scale_f32 v45, vcc, 1.0, v42, 1.0
	v_mul_f32_e32 v46, v45, v44
	v_fma_f32 v47, -v43, v46, v45
	v_fmac_f32_e32 v46, v47, v44
	v_fma_f32 v43, -v43, v46, v45
	v_div_fmas_f32 v43, v43, v44, v46
	v_div_fixup_f32 v42, v43, v42, 1.0
	v_mul_f32_e32 v41, v41, v42
	v_mul_f32_e32 v41, v41, v15
	v_bfe_u32 v43, v41, 16, 1
	v_mul_f32_e32 v40, v40, v42
	v_add3_u32 v41, v41, v43, s22
	v_mul_f32_e32 v40, v40, v16
	ds_write_b16_d16_hi v235, v41 offset:384
	v_bfe_u32 v41, v40, 16, 1
	v_add3_u32 v40, v40, v41, s22
	ds_write_b16_d16_hi v235, v40 offset:448
	v_cmp_gt_f32_e32 vcc, s19, v33
	v_mul_f32_e32 v40, 0x4f800000, v33
	s_nop 0
	v_cndmask_b32_e32 v33, v33, v40, vcc
	v_sqrt_f32_e32 v40, v33
	s_nop 0
	v_add_u32_e32 v41, -1, v40
	v_fma_f32 v42, -v41, v40, v33
	v_cmp_ge_f32_e64 s[82:83], 0, v42
	v_add_u32_e32 v42, 1, v40
	s_nop 0
	v_cndmask_b32_e64 v41, v40, v41, s[82:83]
	v_fma_f32 v40, -v42, v40, v33
	v_cmp_lt_f32_e64 s[82:83], 0, v40
	s_nop 1
	v_cndmask_b32_e64 v40, v41, v42, s[82:83]
	v_mul_f32_e32 v41, 0x37800000, v40
	v_cndmask_b32_e32 v40, v40, v41, vcc
	v_cmp_class_f32_e32 vcc, v33, v234
	s_nop 1
	v_cndmask_b32_e32 v33, v40, v33, vcc
	v_div_scale_f32 v40, s[2:3], v33, v33, 1.0
	v_rcp_f32_e32 v41, v40
	s_nop 0
	v_fma_f32 v42, -v40, v41, 1.0
	v_fmac_f32_e32 v41, v42, v41
	v_div_scale_f32 v42, vcc, 1.0, v33, 1.0
	v_mul_f32_e32 v43, v42, v41
	v_fma_f32 v44, -v40, v43, v42
	v_fmac_f32_e32 v43, v44, v41
	v_fma_f32 v40, -v40, v43, v42
	v_div_fmas_f32 v40, v40, v41, v43
	v_div_fixup_f32 v33, v40, v33, 1.0
	v_mul_f32_e32 v39, v39, v33
	v_mul_f32_e32 v33, v38, v33
	v_mul_f32_e32 v33, v33, v16
	v_bfe_u32 v38, v33, 16, 1
	v_add3_u32 v33, v33, v38, s22
	ds_write_b16_d16_hi v235, v33 offset:1088
	v_cmp_gt_f32_e32 vcc, s19, v32
	v_mul_f32_e32 v33, 0x4f800000, v32
	v_mul_f32_e32 v39, v39, v15
	v_cndmask_b32_e32 v32, v32, v33, vcc
	v_sqrt_f32_e32 v33, v32
	v_bfe_u32 v40, v39, 16, 1
	v_add3_u32 v39, v39, v40, s22
	ds_write_b16_d16_hi v235, v39 offset:1024
	v_add_u32_e32 v38, -1, v33
	v_fma_f32 v39, -v38, v33, v32
	v_cmp_ge_f32_e64 s[82:83], 0, v39
	v_add_u32_e32 v39, 1, v33
	s_nop 0
	v_cndmask_b32_e64 v38, v33, v38, s[82:83]
	v_fma_f32 v33, -v39, v33, v32
	v_cmp_lt_f32_e64 s[82:83], 0, v33
	s_nop 1
	v_cndmask_b32_e64 v33, v38, v39, s[82:83]
	v_mul_f32_e32 v38, 0x37800000, v33
	v_cndmask_b32_e32 v33, v33, v38, vcc
	v_cmp_class_f32_e32 vcc, v32, v234
	s_nop 1
	v_cndmask_b32_e32 v32, v33, v32, vcc
	v_div_scale_f32 v33, s[2:3], v32, v32, 1.0
	v_rcp_f32_e32 v38, v33
	s_nop 0
	v_fma_f32 v39, -v33, v38, 1.0
	v_fmac_f32_e32 v38, v39, v38
	v_div_scale_f32 v39, vcc, 1.0, v32, 1.0
	v_mul_f32_e32 v40, v39, v38
	v_fma_f32 v41, -v33, v40, v39
	v_fmac_f32_e32 v40, v41, v38
	v_fma_f32 v33, -v33, v40, v39
	v_div_fmas_f32 v33, v33, v38, v40
	v_div_fixup_f32 v32, v33, v32, 1.0
	v_mul_f32_e32 v33, v37, v32
	v_mul_f32_e32 v33, v33, v15
	v_bfe_u32 v37, v33, 16, 1
	v_mul_f32_e32 v32, v36, v32
	v_add3_u32 v33, v33, v37, s22
	v_mul_f32_e32 v32, v32, v16
	ds_write_b16_d16_hi v235, v33 offset:1152
	v_bfe_u32 v33, v32, 16, 1
	v_add3_u32 v32, v32, v33, s22
	ds_write_b16_d16_hi v235, v32 offset:1216
	v_cmp_gt_f32_e32 vcc, s19, v31
	v_mul_f32_e32 v32, 0x4f800000, v31
	s_nop 0
	v_cndmask_b32_e32 v31, v31, v32, vcc
	v_sqrt_f32_e32 v32, v31
	s_nop 0
	v_add_u32_e32 v33, -1, v32
	v_fma_f32 v36, -v33, v32, v31
	v_cmp_ge_f32_e64 s[82:83], 0, v36
	v_add_u32_e32 v36, 1, v32
	s_nop 0
	v_cndmask_b32_e64 v33, v32, v33, s[82:83]
	v_fma_f32 v32, -v36, v32, v31
	v_cmp_lt_f32_e64 s[82:83], 0, v32
	s_nop 1
	v_cndmask_b32_e64 v32, v33, v36, s[82:83]
	v_mul_f32_e32 v33, 0x37800000, v32
	v_cndmask_b32_e32 v32, v32, v33, vcc
	v_cmp_class_f32_e32 vcc, v31, v234
	s_nop 1
	v_cndmask_b32_e32 v31, v32, v31, vcc
	v_div_scale_f32 v32, s[2:3], v31, v31, 1.0
	v_rcp_f32_e32 v33, v32
	s_nop 0
	v_fma_f32 v36, -v32, v33, 1.0
	v_fmac_f32_e32 v33, v36, v33
	v_div_scale_f32 v36, vcc, 1.0, v31, 1.0
	v_mul_f32_e32 v37, v36, v33
	v_fma_f32 v38, -v32, v37, v36
	v_fmac_f32_e32 v37, v38, v33
	v_fma_f32 v32, -v32, v37, v36
	v_div_fmas_f32 v32, v32, v33, v37
	v_div_fixup_f32 v31, v32, v31, 1.0
	v_mul_f32_e32 v32, v35, v31
	v_mul_f32_e32 v32, v32, v15
	v_bfe_u32 v33, v32, 16, 1
	v_mul_f32_e32 v31, v34, v31
	v_add3_u32 v32, v32, v33, s22
	v_mul_f32_e32 v31, v31, v16
	ds_write_b16_d16_hi v235, v32 offset:1280
	v_bfe_u32 v32, v31, 16, 1
	v_add3_u32 v31, v31, v32, s22
	ds_write_b16_d16_hi v235, v31 offset:1344
	v_cmp_gt_f32_e32 vcc, s19, v30
	v_mul_f32_e32 v31, 0x4f800000, v30
	s_nop 0
	v_cndmask_b32_e32 v30, v30, v31, vcc
	v_sqrt_f32_e32 v31, v30
	s_nop 0
	v_add_u32_e32 v32, -1, v31
	v_fma_f32 v33, -v32, v31, v30
	v_cmp_ge_f32_e64 s[82:83], 0, v33
	v_add_u32_e32 v33, 1, v31
	s_nop 0
	v_cndmask_b32_e64 v32, v31, v32, s[82:83]
	v_fma_f32 v31, -v33, v31, v30
	v_cmp_lt_f32_e64 s[82:83], 0, v31
	s_nop 1
	v_cndmask_b32_e64 v31, v32, v33, s[82:83]
	v_mul_f32_e32 v32, 0x37800000, v31
	v_cndmask_b32_e32 v31, v31, v32, vcc
	v_cmp_class_f32_e32 vcc, v30, v234
	s_nop 1
	v_cndmask_b32_e32 v30, v31, v30, vcc
	v_div_scale_f32 v31, s[2:3], v30, v30, 1.0
	v_rcp_f32_e32 v32, v31
	s_nop 0
	v_fma_f32 v33, -v31, v32, 1.0
	v_fmac_f32_e32 v32, v33, v32
	v_div_scale_f32 v33, vcc, 1.0, v30, 1.0
	v_mul_f32_e32 v34, v33, v32
	v_fma_f32 v35, -v31, v34, v33
	v_fmac_f32_e32 v34, v35, v32
	v_fma_f32 v31, -v31, v34, v33
	v_div_fmas_f32 v31, v31, v32, v34
	v_div_fixup_f32 v30, v31, v30, 1.0
	v_mul_f32_e32 v24, v24, v30
	v_mul_f32_e32 v24, v24, v15
	v_bfe_u32 v31, v24, 16, 1
	v_mul_f32_e32 v23, v23, v30
	v_add3_u32 v24, v24, v31, s22
	v_mul_f32_e32 v23, v23, v16
	ds_write_b16_d16_hi v235, v24 offset:1408
	v_bfe_u32 v24, v23, 16, 1
	v_add3_u32 v23, v23, v24, s22
	ds_write_b16_d16_hi v235, v23 offset:1472
	v_fmamk_f32 v23, v29, 0x3c800000, v233
	v_cmp_gt_f32_e32 vcc, s19, v23
	v_mul_f32_e32 v24, 0x4f800000, v23
	s_nop 0
	v_cndmask_b32_e32 v23, v23, v24, vcc
	v_sqrt_f32_e32 v24, v23
	s_nop 0
	v_add_u32_e32 v29, -1, v24
	v_fma_f32 v30, -v29, v24, v23
	v_cmp_ge_f32_e64 s[82:83], 0, v30
	v_add_u32_e32 v30, 1, v24
	s_nop 0
	v_cndmask_b32_e64 v29, v24, v29, s[82:83]
	v_fma_f32 v24, -v30, v24, v23
	v_cmp_lt_f32_e64 s[82:83], 0, v24
	s_nop 1
	v_cndmask_b32_e64 v24, v29, v30, s[82:83]
	v_mul_f32_e32 v29, 0x37800000, v24
	v_cndmask_b32_e32 v24, v24, v29, vcc
	v_cmp_class_f32_e32 vcc, v23, v234
	s_nop 1
	v_cndmask_b32_e32 v23, v24, v23, vcc
	v_div_scale_f32 v24, s[2:3], v23, v23, 1.0
	v_rcp_f32_e32 v29, v24
	s_nop 0
	v_fma_f32 v30, -v24, v29, 1.0
	v_fmac_f32_e32 v29, v30, v29
	v_div_scale_f32 v30, vcc, 1.0, v23, 1.0
	v_mul_f32_e32 v31, v30, v29
	v_fma_f32 v32, -v24, v31, v30
	v_fmac_f32_e32 v31, v32, v29
	v_fma_f32 v24, -v24, v31, v30
	v_div_fmas_f32 v24, v24, v29, v31
	v_div_fixup_f32 v23, v24, v23, 1.0
	v_mul_f32_e32 v22, v22, v23
	v_mul_f32_e32 v22, v22, v15
	v_bfe_u32 v24, v22, 16, 1
	v_mul_f32_e32 v21, v21, v23
	v_add3_u32 v22, v22, v24, s22
	v_mul_f32_e32 v21, v21, v16
	ds_write_b16_d16_hi v235, v22 offset:2048
	v_bfe_u32 v22, v21, 16, 1
	v_add3_u32 v21, v21, v22, s22
	ds_write_b16_d16_hi v235, v21 offset:2112
	v_fmamk_f32 v21, v28, 0x3c800000, v233
	v_cmp_gt_f32_e32 vcc, s19, v21
	v_mul_f32_e32 v22, 0x4f800000, v21
	s_nop 0
	v_cndmask_b32_e32 v21, v21, v22, vcc
	v_sqrt_f32_e32 v22, v21
	s_nop 0
	v_add_u32_e32 v23, -1, v22
	v_fma_f32 v24, -v23, v22, v21
	v_cmp_ge_f32_e64 s[82:83], 0, v24
	v_add_u32_e32 v24, 1, v22
	s_nop 0
	v_cndmask_b32_e64 v23, v22, v23, s[82:83]
	v_fma_f32 v22, -v24, v22, v21
	v_cmp_lt_f32_e64 s[82:83], 0, v22
	s_nop 1
	v_cndmask_b32_e64 v22, v23, v24, s[82:83]
	v_mul_f32_e32 v23, 0x37800000, v22
	v_cndmask_b32_e32 v22, v22, v23, vcc
	v_cmp_class_f32_e32 vcc, v21, v234
	s_nop 1
	v_cndmask_b32_e32 v21, v22, v21, vcc
	v_div_scale_f32 v22, s[2:3], v21, v21, 1.0
	v_rcp_f32_e32 v23, v22
	s_nop 0
	v_fma_f32 v24, -v22, v23, 1.0
	v_fmac_f32_e32 v23, v24, v23
	v_div_scale_f32 v24, vcc, 1.0, v21, 1.0
	v_mul_f32_e32 v28, v24, v23
	v_fma_f32 v29, -v22, v28, v24
	v_fmac_f32_e32 v28, v29, v23
	v_fma_f32 v22, -v22, v28, v24
	v_div_fmas_f32 v22, v22, v23, v28
	v_div_fixup_f32 v21, v22, v21, 1.0
	v_mul_f32_e32 v20, v20, v21
	v_mul_f32_e32 v20, v15, v20
	v_bfe_u32 v22, v20, 16, 1
	v_mul_f32_e32 v19, v19, v21
	v_add3_u32 v20, v20, v22, s22
	v_mul_f32_e32 v19, v19, v16
	ds_write_b16_d16_hi v235, v20 offset:2176
	v_bfe_u32 v20, v19, 16, 1
	v_add3_u32 v19, v19, v20, s22
	ds_write_b16_d16_hi v235, v19 offset:2240
	v_fmamk_f32 v19, v27, 0x3c800000, v233
	v_cmp_gt_f32_e32 vcc, s19, v19
	v_mul_f32_e32 v20, 0x4f800000, v19
	s_nop 0
	v_cndmask_b32_e32 v19, v19, v20, vcc
	v_sqrt_f32_e32 v20, v19
	s_nop 0
	v_add_u32_e32 v21, -1, v20
	v_fma_f32 v22, -v21, v20, v19
	v_cmp_ge_f32_e64 s[82:83], 0, v22
	v_add_u32_e32 v22, 1, v20
	s_nop 0
	v_cndmask_b32_e64 v21, v20, v21, s[82:83]
	v_fma_f32 v20, -v22, v20, v19
	v_cmp_lt_f32_e64 s[82:83], 0, v20
	s_nop 1
	v_cndmask_b32_e64 v20, v21, v22, s[82:83]
	v_mul_f32_e32 v21, 0x37800000, v20
	v_cndmask_b32_e32 v20, v20, v21, vcc
	v_cmp_class_f32_e32 vcc, v19, v234
	s_nop 1
	v_cndmask_b32_e32 v19, v20, v19, vcc
	v_div_scale_f32 v20, s[2:3], v19, v19, 1.0
	v_rcp_f32_e32 v21, v20
	s_nop 0
	v_fma_f32 v22, -v20, v21, 1.0
	v_fmac_f32_e32 v21, v22, v21
	v_div_scale_f32 v22, vcc, 1.0, v19, 1.0
	v_mul_f32_e32 v23, v22, v21
	v_fma_f32 v24, -v20, v23, v22
	v_fmac_f32_e32 v23, v24, v21
	v_fma_f32 v20, -v20, v23, v22
	v_div_fmas_f32 v20, v20, v21, v23
	v_div_fixup_f32 v19, v20, v19, 1.0
	v_mul_f32_e32 v18, v18, v19
	v_mul_f32_e32 v18, v15, v18
	v_bfe_u32 v20, v18, 16, 1
	v_mul_f32_e32 v11, v11, v19
	v_add3_u32 v18, v18, v20, s22
	v_mul_f32_e32 v11, v16, v11
	ds_write_b16_d16_hi v235, v18 offset:2304
	v_bfe_u32 v18, v11, 16, 1
	v_add3_u32 v11, v11, v18, s22
	ds_write_b16_d16_hi v235, v11 offset:2368
	v_fmamk_f32 v11, v26, 0x3c800000, v233
	v_cmp_gt_f32_e32 vcc, s19, v11
	v_mul_f32_e32 v18, 0x4f800000, v11
	s_nop 0
	v_cndmask_b32_e32 v11, v11, v18, vcc
	v_sqrt_f32_e32 v18, v11
	s_nop 0
	v_add_u32_e32 v19, -1, v18
	v_fma_f32 v20, -v19, v18, v11
	v_cmp_ge_f32_e64 s[82:83], 0, v20
	v_add_u32_e32 v20, 1, v18
	s_nop 0
	v_cndmask_b32_e64 v19, v18, v19, s[82:83]
	v_fma_f32 v18, -v20, v18, v11
	v_cmp_lt_f32_e64 s[82:83], 0, v18
	s_nop 1
	v_cndmask_b32_e64 v18, v19, v20, s[82:83]
	v_mul_f32_e32 v19, 0x37800000, v18
	v_cndmask_b32_e32 v18, v18, v19, vcc
	v_cmp_class_f32_e32 vcc, v11, v234
	s_nop 1
	v_cndmask_b32_e32 v11, v18, v11, vcc
	v_div_scale_f32 v18, s[2:3], v11, v11, 1.0
	v_rcp_f32_e32 v19, v18
	s_nop 0
	v_fma_f32 v20, -v18, v19, 1.0
	v_fmac_f32_e32 v19, v20, v19
	v_div_scale_f32 v20, vcc, 1.0, v11, 1.0
	v_mul_f32_e32 v21, v20, v19
	v_fma_f32 v22, -v18, v21, v20
	v_fmac_f32_e32 v21, v22, v19
	v_fma_f32 v18, -v18, v21, v20
	v_div_fmas_f32 v18, v18, v19, v21
	v_div_fixup_f32 v11, v18, v11, 1.0
	v_mul_f32_e32 v7, v7, v11
	v_mul_f32_e32 v7, v15, v7
	v_bfe_u32 v18, v7, 16, 1
	v_mul_f32_e32 v6, v6, v11
	v_add3_u32 v7, v7, v18, s22
	v_mul_f32_e32 v6, v16, v6
	ds_write_b16_d16_hi v235, v7 offset:2432
	v_bfe_u32 v7, v6, 16, 1
	v_add3_u32 v6, v6, v7, s22
	ds_write_b16_d16_hi v235, v6 offset:2496
	v_fmamk_f32 v6, v25, 0x3c800000, v233
	v_cmp_gt_f32_e32 vcc, s19, v6
	v_mul_f32_e32 v7, 0x4f800000, v6
	s_nop 0
	v_cndmask_b32_e32 v6, v6, v7, vcc
	v_sqrt_f32_e32 v7, v6
	s_nop 0
	v_add_u32_e32 v11, -1, v7
	v_fma_f32 v18, -v11, v7, v6
	v_cmp_ge_f32_e64 s[82:83], 0, v18
	v_add_u32_e32 v18, 1, v7
	s_nop 0
	v_cndmask_b32_e64 v11, v7, v11, s[82:83]
	v_fma_f32 v7, -v18, v7, v6
	v_cmp_lt_f32_e64 s[82:83], 0, v7
	s_nop 1
	v_cndmask_b32_e64 v7, v11, v18, s[82:83]
	v_mul_f32_e32 v11, 0x37800000, v7
	v_cndmask_b32_e32 v7, v7, v11, vcc
	v_cmp_class_f32_e32 vcc, v6, v234
	s_nop 1
	v_cndmask_b32_e32 v6, v7, v6, vcc
	v_div_scale_f32 v7, s[2:3], v6, v6, 1.0
	v_rcp_f32_e32 v11, v7
	s_nop 0
	v_fma_f32 v18, -v7, v11, 1.0
	v_fmac_f32_e32 v11, v18, v11
	v_div_scale_f32 v18, vcc, 1.0, v6, 1.0
	v_mul_f32_e32 v19, v18, v11
	v_fma_f32 v20, -v7, v19, v18
	v_fmac_f32_e32 v19, v20, v11
	v_fma_f32 v7, -v7, v19, v18
	v_div_fmas_f32 v7, v7, v11, v19
	v_div_fixup_f32 v6, v7, v6, 1.0
	v_mul_f32_e32 v7, v12, v6
	v_mul_f32_e32 v7, v15, v7
	v_bfe_u32 v11, v7, 16, 1
	v_mul_f32_e32 v6, v10, v6
	v_add3_u32 v7, v7, v11, s22
	v_mul_f32_e32 v6, v16, v6
	ds_write_b16_d16_hi v235, v7 offset:3072
	v_bfe_u32 v7, v6, 16, 1
	v_add3_u32 v6, v6, v7, s22
	ds_write_b16_d16_hi v235, v6 offset:3136
	v_fmamk_f32 v6, v17, 0x3c800000, v233
	v_cmp_gt_f32_e32 vcc, s19, v6
	v_mul_f32_e32 v7, 0x4f800000, v6
	s_nop 0
	v_cndmask_b32_e32 v6, v6, v7, vcc
	v_sqrt_f32_e32 v7, v6
	s_nop 0
	v_add_u32_e32 v10, -1, v7
	v_fma_f32 v11, -v10, v7, v6
	v_cmp_ge_f32_e64 s[82:83], 0, v11
	v_add_u32_e32 v11, 1, v7
	s_nop 0
	v_cndmask_b32_e64 v10, v7, v10, s[82:83]
	v_fma_f32 v7, -v11, v7, v6
	v_cmp_lt_f32_e64 s[82:83], 0, v7
	s_nop 1
	v_cndmask_b32_e64 v7, v10, v11, s[82:83]
	v_mul_f32_e32 v10, 0x37800000, v7
	v_cndmask_b32_e32 v7, v7, v10, vcc
	v_cmp_class_f32_e32 vcc, v6, v234
	s_nop 1
	v_cndmask_b32_e32 v6, v7, v6, vcc
	v_div_scale_f32 v7, s[2:3], v6, v6, 1.0
	v_rcp_f32_e32 v10, v7
	s_nop 0
	v_fma_f32 v11, -v7, v10, 1.0
	v_fmac_f32_e32 v10, v11, v10
	v_div_scale_f32 v11, vcc, 1.0, v6, 1.0
	v_mul_f32_e32 v12, v11, v10
	v_fma_f32 v17, -v7, v12, v11
	v_fmac_f32_e32 v12, v17, v10
	v_fma_f32 v7, -v7, v12, v11
	v_div_fmas_f32 v7, v7, v10, v12
	v_div_fixup_f32 v6, v7, v6, 1.0
	v_mul_f32_e32 v7, v9, v6
	v_mul_f32_e32 v7, v15, v7
	v_bfe_u32 v9, v7, 16, 1
	v_mul_f32_e32 v6, v8, v6
	v_add3_u32 v7, v7, v9, s22
	v_mul_f32_e32 v6, v16, v6
	ds_write_b16_d16_hi v235, v7 offset:3200
	v_bfe_u32 v7, v6, 16, 1
	v_add3_u32 v6, v6, v7, s22
	ds_write_b16_d16_hi v235, v6 offset:3264
	v_fmamk_f32 v6, v14, 0x3c800000, v233
	v_cmp_gt_f32_e32 vcc, s19, v6
	v_mul_f32_e32 v7, 0x4f800000, v6
	s_nop 0
	v_cndmask_b32_e32 v6, v6, v7, vcc
	v_sqrt_f32_e32 v7, v6
	s_nop 0
	v_add_u32_e32 v8, -1, v7
	v_fma_f32 v9, -v8, v7, v6
	v_cmp_ge_f32_e64 s[82:83], 0, v9
	v_add_u32_e32 v9, 1, v7
	s_nop 0
	v_cndmask_b32_e64 v8, v7, v8, s[82:83]
	v_fma_f32 v7, -v9, v7, v6
	v_cmp_lt_f32_e64 s[82:83], 0, v7
	s_nop 1
	v_cndmask_b32_e64 v7, v8, v9, s[82:83]
	v_mul_f32_e32 v8, 0x37800000, v7
	v_cndmask_b32_e32 v7, v7, v8, vcc
	v_cmp_class_f32_e32 vcc, v6, v234
	s_nop 1
	v_cndmask_b32_e32 v6, v7, v6, vcc
	v_div_scale_f32 v7, s[2:3], v6, v6, 1.0
	v_rcp_f32_e32 v8, v7
	s_nop 0
	v_fma_f32 v9, -v7, v8, 1.0
	v_fmac_f32_e32 v8, v9, v8
	v_div_scale_f32 v9, vcc, 1.0, v6, 1.0
	v_mul_f32_e32 v10, v9, v8
	v_fma_f32 v11, -v7, v10, v9
	v_fmac_f32_e32 v10, v11, v8
	v_fma_f32 v7, -v7, v10, v9
	v_div_fmas_f32 v7, v7, v8, v10
	v_div_fixup_f32 v6, v7, v6, 1.0
	v_mul_f32_e32 v5, v5, v6
	v_mul_f32_e32 v5, v15, v5
	v_bfe_u32 v7, v5, 16, 1
	v_mul_f32_e32 v4, v4, v6
	v_add3_u32 v5, v5, v7, s22
	v_mul_f32_e32 v4, v16, v4
	ds_write_b16_d16_hi v235, v5 offset:3328
	v_bfe_u32 v5, v4, 16, 1
	v_add3_u32 v4, v4, v5, s22
	ds_write_b16_d16_hi v235, v4 offset:3392
	v_fmamk_f32 v4, v13, 0x3c800000, v233
	v_cmp_gt_f32_e32 vcc, s19, v4
	v_mul_f32_e32 v5, 0x4f800000, v4
	s_nop 0
	v_cndmask_b32_e32 v4, v4, v5, vcc
	v_sqrt_f32_e32 v5, v4
	s_nop 0
	v_add_u32_e32 v6, -1, v5
	v_fma_f32 v7, -v6, v5, v4
	v_cmp_ge_f32_e64 s[82:83], 0, v7
	v_add_u32_e32 v7, 1, v5
	s_nop 0
	v_cndmask_b32_e64 v6, v5, v6, s[82:83]
	v_fma_f32 v5, -v7, v5, v4
	v_cmp_lt_f32_e64 s[82:83], 0, v5
	s_nop 1
	v_cndmask_b32_e64 v5, v6, v7, s[82:83]
	v_mul_f32_e32 v6, 0x37800000, v5
	v_cndmask_b32_e32 v5, v5, v6, vcc
	v_cmp_class_f32_e32 vcc, v4, v234
	s_nop 1
	v_cndmask_b32_e32 v4, v5, v4, vcc
	v_div_scale_f32 v5, s[2:3], v4, v4, 1.0
	v_rcp_f32_e32 v6, v5
	s_add_u32 s2, s16, s23
	s_addc_u32 s3, s17, 0
	v_fma_f32 v7, -v5, v6, 1.0
	v_fmac_f32_e32 v6, v7, v6
	v_div_scale_f32 v7, vcc, 1.0, v4, 1.0
	v_mul_f32_e32 v8, v7, v6
	v_fma_f32 v9, -v5, v8, v7
	v_fmac_f32_e32 v8, v9, v6
	v_fma_f32 v5, -v5, v8, v7
	v_div_fmas_f32 v5, v5, v6, v8
	v_div_fixup_f32 v4, v5, v4, 1.0
	v_mul_f32_e32 v3, v3, v4
	v_mul_f32_e32 v3, v15, v3
	v_bfe_u32 v5, v3, 16, 1
	v_mul_f32_e32 v2, v2, v4
	v_add3_u32 v3, v3, v5, s22
	v_mul_f32_e32 v2, v16, v2
	ds_write_b16_d16_hi v235, v3 offset:3456
	v_bfe_u32 v3, v2, 16, 1
	v_add3_u32 v2, v2, v3, s22
	ds_write_b16_d16_hi v235, v2 offset:3520
	s_waitcnt lgkmcnt(0)
	ds_read_b128 v[2:5], v236
	v_mov_b32_e32 v9, s3
	v_or_b32_e32 v8, s2, v176
	v_lshl_add_u64 v[6:7], v[178:179], 0, s[14:15]
	v_lshlrev_b64 v[8:9], 11, v[8:9]
	v_lshl_add_u64 v[8:9], v[6:7], 0, v[8:9]
	s_waitcnt lgkmcnt(0)
	global_store_dwordx4 v[8:9], v[2:5], off
	ds_read_b128 v[2:5], v237
	v_mov_b32_e32 v9, s3
	v_or_b32_e32 v8, s2, v180
	v_lshlrev_b64 v[8:9], 11, v[8:9]
	v_lshl_add_u64 v[8:9], v[6:7], 0, v[8:9]
	s_waitcnt lgkmcnt(0)
	global_store_dwordx4 v[8:9], v[2:5], off
	ds_read_b128 v[2:5], v238
	v_mov_b32_e32 v9, s3
	v_or_b32_e32 v8, s2, v182
	v_lshlrev_b64 v[8:9], 11, v[8:9]
	v_lshl_add_u64 v[8:9], v[6:7], 0, v[8:9]
	s_waitcnt lgkmcnt(0)
	global_store_dwordx4 v[8:9], v[2:5], off
	ds_read_b128 v[2:5], v239
	v_mov_b32_e32 v9, s3
	v_or_b32_e32 v8, s2, v184
	v_lshlrev_b64 v[8:9], 11, v[8:9]
	v_lshl_add_u64 v[6:7], v[6:7], 0, v[8:9]
	s_waitcnt lgkmcnt(0)
	global_store_dwordx4 v[6:7], v[2:5], off
	s_waitcnt vmcnt(0) lgkmcnt(0)
	s_barrier
	s_mov_b64 s[2:3], 0

.LBB0_653:
	s_waitcnt vmcnt(0)
	s_barrier
	s_and_saveexec_b64 s[2:3], s[0:1]
	s_cbranch_execz .LBB0_655
	s_cmp_eq_u32 s100, 0
	s_cbranch_scc1 .Lfox_first
	v_mov_b32_e32 v2, v254
	s_branch .Lfox_got
.Lfox_first:
	global_atomic_add v2, v175, v231, s[6:7] sc0
.Lfox_got:
	v_mov_b32_e32 v3, s18
	s_waitcnt vmcnt(0)
	ds_write_b32 v3, v2

	.amdhsa_kernel _Z6mk_fwd4Args
		.amdhsa_group_segment_fixed_size 0
		.amdhsa_private_segment_fixed_size 0
		.amdhsa_kernarg_size 504
		.amdhsa_user_sgpr_count 2
		.amdhsa_user_sgpr_dispatch_ptr 0
		.amdhsa_user_sgpr_queue_ptr 0
		.amdhsa_user_sgpr_kernarg_segment_ptr 1
		.amdhsa_user_sgpr_dispatch_id 0
		.amdhsa_user_sgpr_kernarg_preload_length 0
		.amdhsa_user_sgpr_kernarg_preload_offset 0
		.amdhsa_user_sgpr_private_segment_size 0
		.amdhsa_uses_dynamic_stack 0
		.amdhsa_enable_private_segment 0
		.amdhsa_system_sgpr_workgroup_id_x 1
		.amdhsa_system_sgpr_workgroup_id_y 0
		.amdhsa_system_sgpr_workgroup_id_z 0
		.amdhsa_system_sgpr_workgroup_info 0
		.amdhsa_system_vgpr_workitem_id 0
		.amdhsa_next_free_vgpr 256
		.amdhsa_next_free_sgpr 102
		.amdhsa_accum_offset 256
		.amdhsa_reserve_vcc 1
		.amdhsa_float_round_mode_32 0
		.amdhsa_float_round_mode_16_64 0
		.amdhsa_float_denorm_mode_32 3
		.amdhsa_float_denorm_mode_16_64 3
		.amdhsa_dx10_clamp 1
		.amdhsa_ieee_mode 1
		.amdhsa_fp16_overflow 0
		.amdhsa_tg_split 0
		.amdhsa_exception_fp_ieee_invalid_op 0
		.amdhsa_exception_fp_denorm_src 0
		.amdhsa_exception_fp_ieee_div_zero 0
		.amdhsa_exception_fp_ieee_overflow 0
		.amdhsa_exception_fp_ieee_underflow 0
		.amdhsa_exception_fp_ieee_inexact 0
		.amdhsa_exception_int_div_zero 0
	.end_amdhsa_kernel

amdhsa.kernels:
  - .agpr_count:     0
    .args:
      - .offset:         0
        .size:           248
        .value_kind:     by_value
      - .offset:         248
        .size:           4
        .value_kind:     hidden_block_count_x
      - .offset:         252
        .size:           4
        .value_kind:     hidden_block_count_y
      - .offset:         256
        .size:           4
        .value_kind:     hidden_block_count_z
      - .offset:         260
        .size:           2
        .value_kind:     hidden_group_size_x
      - .offset:         262
        .size:           2
        .value_kind:     hidden_group_size_y
      - .offset:         264
        .size:           2
        .value_kind:     hidden_group_size_z
      - .offset:         266
        .size:           2
        .value_kind:     hidden_remainder_x
      - .offset:         268
        .size:           2
        .value_kind:     hidden_remainder_y
      - .offset:         270
        .size:           2
        .value_kind:     hidden_remainder_z
      - .offset:         288
        .size:           8
        .value_kind:     hidden_global_offset_x
      - .offset:         296
        .size:           8
        .value_kind:     hidden_global_offset_y
      - .offset:         304
        .size:           8
        .value_kind:     hidden_global_offset_z
      - .offset:         312
        .size:           2
        .value_kind:     hidden_grid_dims
      - .offset:         368
        .size:           4
        .value_kind:     hidden_dynamic_lds_size
    .group_segment_fixed_size: 0
    .kernarg_segment_align: 8
    .kernarg_segment_size: 504
    .language:       OpenCL C
    .language_version:
      - 2
      - 0
    .max_flat_workgroup_size: 512
    .name:           _Z6mk_fwd4Args
    .private_segment_fixed_size: 0
    .sgpr_count:     108
    .sgpr_spill_count: 130
    .symbol:         _Z6mk_fwd4Args.kd
    .uniform_work_group_size: 1
    .uses_dynamic_stack: false
    .vgpr_count:     256
    .vgpr_spill_count: 0
    .wavefront_size: 64
  - .agpr_count:     0
    .args:
      - .address_space:  global
        .offset:         0
        .size:           8
        .value_kind:     global_buffer
      - .address_space:  global
        .offset:         8
        .size:           8
        .value_kind:     global_buffer
    .group_segment_fixed_size: 0
    .kernarg_segment_align: 8
    .kernarg_segment_size: 16
    .language:       OpenCL C
    .language_version:
      - 2
      - 0
    .max_flat_workgroup_size: 1024
    .name:           _Z11unpack_ofoxPKtPf
    .private_segment_fixed_size: 0
    .sgpr_count:     14
    .sgpr_spill_count: 0
    .symbol:         _Z11unpack_ofoxPKtPf.kd
    .uniform_work_group_size: 1
    .uses_dynamic_stack: false
    .vgpr_count:     8
    .vgpr_spill_count: 0
    .wavefront_size: 64
